# prompt SSM scan: next-chunk address calc + 3 LDS-DMA issues moved from the loop head into the shadows of the four B.x MFMAs (lever 8); on top of scan diet + 0x6000 split
# baseline (speedup 1.0000x reference)
.LBB0_87:
	v_add_u32_e32 v184, s3, v136
	v_mov_b64_e32 v[108:109], v[100:101]
	v_mov_b64_e32 v[112:113], v[104:105]
	v_mov_b64_e32 v[106:107], v[98:99]
	v_mov_b32_e32 v133, v125
	v_mov_b64_e32 v[110:111], v[102:103]
	v_mov_b32_e32 v10, v178
	v_mov_b32_e32 v182, v156
	v_mov_b32_e32 v180, v150
	s_cmp_lt_i32 s3, 0
	s_cbranch_scc1 .Lssm_warm
	v_pk_mul_f32 v[6:7], v[6:7], v[10:11] op_sel_hi:[1,0]
	v_pk_mul_f32 v[8:9], v[8:9], v[10:11] op_sel_hi:[1,0]
	v_pk_mul_f32 v[2:3], v[10:11], v[2:3] op_sel_hi:[0,1]
	v_pk_mul_f32 v[4:5], v[10:11], v[4:5] op_sel_hi:[0,1]
	v_cvt_pk_bf16_f32 v50, v6, v7
	v_cvt_pk_bf16_f32 v51, v8, v9
	v_cvt_pk_bf16_f32 v52, v2, v3
	v_cvt_pk_bf16_f32 v53, v4, v5
	v_mov_b32_e32 v186, v177
	v_mov_b32_e32 v187, v176
	v_mfma_f32_32x32x16_bf16 v[2:17], v[50:53], v[94:97], 0
	v_add_u32_e32 v234, s3, v162
	v_add_u32_e32 v226, 96, v234
	v_mov_b32_e32 v222, s10
	v_mov_b32_e32 v223, s8
	v_add_u32_e32 v227, 0xffffe060, v234
	v_cmp_gt_i32_e32 vcc, s26, v226
	v_ashrrev_i32_e32 v228, 31, v226
	v_mov_b32_e32 v224, s11
	v_mov_b32_e32 v225, s9
	v_cndmask_b32_e32 v230, v222, v223, vcc
	v_cndmask_b32_e32 v222, v227, v226, vcc
	v_cndmask_b32_e32 v223, 0, v228, vcc
	v_cndmask_b32_e32 v231, v224, v225, vcc
	v_lshlrev_b64 v[232:233], 14, v[222:223]
	v_lshl_add_u64 v[230:231], v[230:231], 0, v[232:233]
	v_lshl_add_u64 v[200:201], v[230:231], 0, s[36:37]
	v_lshl_add_u64 v[200:201], v[200:201], 0, v[124:125]
	v_mov_b32_e32 v188, v165
	v_mov_b32_e32 v189, v164
	v_add_u32_e32 v197, 0x800, v191
	v_add_u32_e32 v196, 0xa00, v191
	v_add_u32_e32 v195, 0x1000, v191
	v_add_u32_e32 v194, 0x1400, v191
	v_add_u32_e32 v163, 0x1800, v191
	v_mfma_f32_32x32x16_bf16 v[34:49], v[50:53], v[90:93], 0
	s_add_i32 m0, s100, 0x1000
	s_nop 0
	global_load_lds_dword v[174:175], off
	s_nop 3
	v_mov_b32_e32 v198, v2
	v_mov_b32_e32 v2, v4
	v_mov_b32_e32 v4, v6
	v_mov_b32_e32 v6, v8
	v_add_u32_e32 v193, 0x1a00, v191
	v_add_u32_e32 v137, 0x1c00, v191
	s_nop 1
	v_mov_b32_e32 v199, v34
	v_mfma_f32_32x32x16_bf16 v[18:33], v[50:53], v[86:89], 0
	s_add_i32 m0, s100, 0x3f0
	s_nop 0
	global_load_lds_dwordx4 v[200:201], off offset:16
	v_mov_b32_e32 v34, v3
	v_mov_b32_e32 v3, v36
	v_mov_b32_e32 v36, v5
	v_mov_b32_e32 v5, v38
	v_mov_b32_e32 v38, v7
	v_mov_b32_e32 v7, v40
	v_mov_b32_e32 v8, v41
	v_mfma_f32_32x32x16_bf16 v[50:65], v[50:53], v[82:85], 0
	s_add_i32 m0, s100, 0x0
	s_nop 0
	global_load_lds_dwordx4 v[200:201], off
	s_nop 0
	s_add_i32 s98, s98, 0x1400
	s_cmp_eq_u32 s98, 0x7800
	s_cselect_b32 s98, 0, s98
	s_add_i32 s100, s99, s98
	v_mov_b32_e32 v40, v10
	v_mov_b32_e32 v41, v42
	v_mov_b32_e32 v10, v43
	v_mov_b32_e32 v42, v12
	v_mov_b32_e32 v43, v44
	v_mov_b32_e32 v12, v45
	v_mov_b32_e32 v44, v14
	v_mov_b32_e32 v45, v46
	v_mov_b32_e32 v14, v47
	v_mov_b32_e32 v46, v16
	v_mov_b32_e32 v47, v48
	v_mov_b32_e32 v16, v49
	v_mov_b32_e32 v48, v18
	v_mov_b32_e32 v49, v50
	v_mov_b32_e32 v50, v19
	v_mov_b32_e32 v18, v20
	v_mov_b32_e32 v19, v52
	v_mov_b32_e32 v52, v21
	v_mov_b32_e32 v20, v22
	v_mov_b32_e32 v21, v54
	v_mov_b32_e32 v54, v23
	v_mov_b32_e32 v22, v24
	v_mov_b32_e32 v23, v56
	v_mov_b32_e32 v24, v57
	v_mov_b32_e32 v56, v26
	v_mov_b32_e32 v57, v58
	v_mov_b32_e32 v26, v59
	v_mov_b32_e32 v58, v28
	v_mov_b32_e32 v59, v60
	v_mov_b32_e32 v28, v61
	v_mov_b32_e32 v60, v30
	v_mov_b32_e32 v61, v62
	v_mov_b32_e32 v30, v63
	v_mov_b32_e32 v62, v32
	v_mov_b32_e32 v63, v64
	v_mov_b32_e32 v32, v65
	v_pk_fma_f32 v[64:65], v[148:149], v[176:177], v[198:199]
	v_pk_fma_f32 v[48:49], v[142:143], v[164:165], v[48:49]
	v_pk_fma_f32 v[64:65], v[160:161], v[186:187], v[64:65]
	v_pk_fma_f32 v[48:49], v[152:153], v[188:189], v[48:49]
	v_pk_fma_f32 v[34:35], v[148:149], v[64:65], v[34:35]
	v_pk_fma_f32 v[50:51], v[142:143], v[48:49], v[50:51]
	v_cvt_pk_bf16_f32 v164, v48, v49
	v_pk_fma_f32 v[34:35], v[160:161], v[64:65], v[34:35] op_sel:[0,1,0] op_sel_hi:[1,0,1]
	v_pk_fma_f32 v[48:49], v[152:153], v[48:49], v[50:51] op_sel:[0,1,0] op_sel_hi:[1,0,1]
	v_pk_fma_f32 v[2:3], v[148:149], v[34:35], v[2:3]
	v_pk_fma_f32 v[18:19], v[142:143], v[48:49], v[18:19]
	v_pk_fma_f32 v[2:3], v[160:161], v[34:35], v[2:3] op_sel:[0,1,0] op_sel_hi:[1,0,1]
	v_pk_fma_f32 v[18:19], v[152:153], v[48:49], v[18:19] op_sel:[0,1,0] op_sel_hi:[1,0,1]
	v_cvt_pk_bf16_f32 v50, v34, v35
	v_pk_fma_f32 v[34:35], v[148:149], v[2:3], v[36:37]
	v_pk_fma_f32 v[36:37], v[142:143], v[18:19], v[52:53]
	v_cvt_pk_bf16_f32 v51, v48, v49
	v_cvt_pk_bf16_f32 v48, v2, v3
	v_cvt_pk_bf16_f32 v49, v18, v19
	v_pk_fma_f32 v[2:3], v[160:161], v[2:3], v[34:35] op_sel:[0,1,0] op_sel_hi:[1,0,1]
	v_pk_fma_f32 v[18:19], v[152:153], v[18:19], v[36:37] op_sel:[0,1,0] op_sel_hi:[1,0,1]
	v_pk_fma_f32 v[4:5], v[148:149], v[2:3], v[4:5]
	v_pk_fma_f32 v[20:21], v[142:143], v[18:19], v[20:21]
	v_cvt_pk_bf16_f32 v34, v2, v3
	v_pk_fma_f32 v[2:3], v[160:161], v[2:3], v[4:5] op_sel:[0,1,0] op_sel_hi:[1,0,1]
	v_pk_fma_f32 v[4:5], v[152:153], v[18:19], v[20:21] op_sel:[0,1,0] op_sel_hi:[1,0,1]
	v_cvt_pk_bf16_f32 v35, v18, v19
	v_pk_fma_f32 v[18:19], v[148:149], v[2:3], v[38:39]
	v_pk_fma_f32 v[20:21], v[142:143], v[4:5], v[54:55]
	ds_write2_b32 v191, v34, v35 offset0:204 offset1:236
	v_cvt_pk_bf16_f32 v34, v2, v3
	v_cvt_pk_bf16_f32 v35, v4, v5
	v_pk_fma_f32 v[2:3], v[160:161], v[2:3], v[18:19] op_sel:[0,1,0] op_sel_hi:[1,0,1]
	v_pk_fma_f32 v[4:5], v[152:153], v[4:5], v[20:21] op_sel:[0,1,0] op_sel_hi:[1,0,1]
	v_pk_fma_f32 v[6:7], v[148:149], v[2:3], v[6:7]
	v_pk_fma_f32 v[18:19], v[142:143], v[4:5], v[22:23]
	v_cvt_pk_bf16_f32 v20, v2, v3
	v_cvt_pk_bf16_f32 v21, v4, v5
	v_pk_fma_f32 v[2:3], v[158:159], v[2:3], v[6:7] op_sel:[0,0,1] op_sel_hi:[1,1,0]
	v_pk_fma_f32 v[4:5], v[146:147], v[4:5], v[18:19] op_sel:[0,0,1] op_sel_hi:[1,1,0]
	ds_write2_b32 v197, v20, v21 offset0:100 offset1:132
	v_pk_mov_b32 v[6:7], v[2:3], v[2:3] op_sel:[1,0]
	v_pk_fma_f32 v[8:9], v[148:149], v[2:3], v[8:9]
	v_pk_mov_b32 v[18:19], v[4:5], v[4:5] op_sel:[1,0]
	v_pk_fma_f32 v[20:21], v[142:143], v[4:5], v[24:25]
	v_cvt_pk_bf16_f32 v22, v6, v7
	v_pk_fma_f32 v[2:3], v[166:167], v[2:3], v[8:9] op_sel:[0,0,1] op_sel_hi:[1,1,0]
	v_cvt_pk_bf16_f32 v8, v18, v19
	v_pk_fma_f32 v[4:5], v[168:169], v[4:5], v[20:21] op_sel:[0,0,1] op_sel_hi:[1,1,0]
	v_pk_fma_f32 v[6:7], v[148:149], v[2:3], v[40:41]
	ds_write2_b32 v197, v22, v8 offset0:168 offset1:200
	v_pk_fma_f32 v[8:9], v[142:143], v[4:5], v[56:57]
	v_cvt_pk_bf16_f32 v18, v2, v3
	v_cvt_pk_bf16_f32 v19, v4, v5
	v_pk_fma_f32 v[2:3], v[158:159], v[2:3], v[6:7] op_sel:[0,0,1] op_sel_hi:[1,1,0]
	v_pk_fma_f32 v[4:5], v[146:147], v[4:5], v[8:9] op_sel:[0,0,1] op_sel_hi:[1,1,0]
	ds_write2_b32 v196, v18, v19 offset0:108 offset1:140
	v_pk_mov_b32 v[6:7], v[2:3], v[2:3] op_sel:[1,0]
	v_pk_fma_f32 v[8:9], v[148:149], v[2:3], v[10:11]
	v_pk_mov_b32 v[10:11], v[4:5], v[4:5] op_sel:[1,0]
	v_pk_fma_f32 v[18:19], v[142:143], v[4:5], v[26:27]
	v_cvt_pk_bf16_f32 v20, v6, v7
	v_pk_fma_f32 v[2:3], v[166:167], v[2:3], v[8:9] op_sel:[0,0,1] op_sel_hi:[1,1,0]
	v_cvt_pk_bf16_f32 v8, v10, v11
	v_pk_fma_f32 v[4:5], v[168:169], v[4:5], v[18:19] op_sel:[0,0,1] op_sel_hi:[1,1,0]
	v_pk_fma_f32 v[6:7], v[148:149], v[2:3], v[42:43]
	ds_write2_b32 v195, v20, v8 offset0:64 offset1:96
	v_pk_fma_f32 v[8:9], v[142:143], v[4:5], v[58:59]
	v_cvt_pk_bf16_f32 v10, v2, v3
	v_cvt_pk_bf16_f32 v11, v4, v5
	v_pk_fma_f32 v[2:3], v[158:159], v[2:3], v[6:7] op_sel:[0,0,1] op_sel_hi:[1,1,0]
	v_pk_fma_f32 v[4:5], v[146:147], v[4:5], v[8:9] op_sel:[0,0,1] op_sel_hi:[1,1,0]
	ds_write2_b32 v195, v10, v11 offset0:132 offset1:164
	v_pk_mov_b32 v[6:7], v[2:3], v[2:3] op_sel:[1,0]
	v_pk_fma_f32 v[8:9], v[148:149], v[2:3], v[12:13]
	v_pk_mov_b32 v[10:11], v[4:5], v[4:5] op_sel:[1,0]
	v_pk_fma_f32 v[12:13], v[142:143], v[4:5], v[28:29]
	v_cvt_pk_bf16_f32 v18, v6, v7
	v_pk_fma_f32 v[2:3], v[166:167], v[2:3], v[8:9] op_sel:[0,0,1] op_sel_hi:[1,1,0]
	v_cvt_pk_bf16_f32 v8, v10, v11
	v_pk_fma_f32 v[4:5], v[168:169], v[4:5], v[12:13] op_sel:[0,0,1] op_sel_hi:[1,1,0]
	v_pk_fma_f32 v[6:7], v[148:149], v[2:3], v[44:45]
	ds_write2_b32 v195, v18, v8 offset0:200 offset1:232
	v_pk_fma_f32 v[8:9], v[142:143], v[4:5], v[60:61]
	v_cvt_pk_bf16_f32 v10, v2, v3
	v_cvt_pk_bf16_f32 v11, v4, v5
	v_pk_fma_f32 v[2:3], v[158:159], v[2:3], v[6:7] op_sel:[0,0,1] op_sel_hi:[1,1,0]
	v_pk_fma_f32 v[4:5], v[146:147], v[4:5], v[8:9] op_sel:[0,0,1] op_sel_hi:[1,1,0]
	ds_write2_b32 v194, v10, v11 offset0:12 offset1:44
	v_pk_mov_b32 v[6:7], v[2:3], v[2:3] op_sel:[1,0]
	v_pk_fma_f32 v[8:9], v[148:149], v[2:3], v[14:15]
	v_pk_mov_b32 v[10:11], v[4:5], v[4:5] op_sel:[1,0]
	v_pk_fma_f32 v[12:13], v[142:143], v[4:5], v[30:31]
	v_cvt_pk_bf16_f32 v14, v6, v7
	v_pk_fma_f32 v[2:3], v[166:167], v[2:3], v[8:9] op_sel:[0,0,1] op_sel_hi:[1,1,0]
	v_cvt_pk_bf16_f32 v8, v10, v11
	v_pk_fma_f32 v[4:5], v[168:169], v[4:5], v[12:13] op_sel:[0,0,1] op_sel_hi:[1,1,0]
	v_pk_fma_f32 v[6:7], v[148:149], v[2:3], v[46:47]
	ds_write2_b32 v163, v14, v8 offset0:96 offset1:128
	v_pk_fma_f32 v[8:9], v[142:143], v[4:5], v[62:63]
	v_cvt_pk_bf16_f32 v10, v2, v3
	v_cvt_pk_bf16_f32 v11, v4, v5
	v_pk_fma_f32 v[2:3], v[158:159], v[2:3], v[6:7] op_sel:[0,0,1] op_sel_hi:[1,1,0]
	v_pk_fma_f32 v[4:5], v[146:147], v[4:5], v[8:9] op_sel:[0,0,1] op_sel_hi:[1,1,0]
	v_cvt_pk_bf16_f32 v133, v64, v65
	ds_write2_b32 v163, v10, v11 offset0:164 offset1:196
	v_pk_mov_b32 v[6:7], v[2:3], v[2:3] op_sel:[1,0]
	v_pk_fma_f32 v[8:9], v[148:149], v[2:3], v[16:17]
	v_pk_mov_b32 v[10:11], v[4:5], v[4:5] op_sel:[1,0]
	v_pk_fma_f32 v[12:13], v[142:143], v[4:5], v[32:33]
	ds_write2_b32 v191, v133, v164 offset1:32
	v_cvt_pk_bf16_f32 v6, v6, v7
	v_pk_fma_f32 v[176:177], v[166:167], v[2:3], v[8:9] op_sel:[0,0,1] op_sel_hi:[1,1,0]
	v_cvt_pk_bf16_f32 v2, v10, v11
	v_pk_fma_f32 v[164:165], v[168:169], v[4:5], v[12:13] op_sel:[0,0,1] op_sel_hi:[1,1,0]
	v_cvt_pk_bf16_f32 v3, v176, v177
	ds_write2_b32 v193, v6, v2 offset0:104 offset1:136
	v_cvt_pk_bf16_f32 v2, v164, v165
	ds_write2_b32 v191, v50, v51 offset0:68 offset1:100
	ds_write2_b32 v191, v48, v49 offset0:136 offset1:168
	ds_write2_b32 v197, v34, v35 offset0:32 offset1:64
	ds_write2_b32 v137, v3, v2 offset0:44 offset1:76
	s_waitcnt lgkmcnt(0)
	ds_read_b128 v[18:21], v192
	ds_read_b128 v[22:25], v192 offset:4352
	ds_read_b128 v[26:29], v192 offset:64
	ds_read_b128 v[30:33], v192 offset:4416
	ds_read_b128 v[34:37], v192 offset:128
	ds_read_b128 v[38:41], v192 offset:4480
	ds_read_b128 v[42:45], v192 offset:192
	ds_read_b128 v[46:49], v192 offset:4544
	s_waitcnt lgkmcnt(6)
	v_mfma_f32_16x16x32_bf16 v[2:5], v[74:77], v[18:21], 0
	v_mfma_f32_16x16x32_bf16 v[6:9], v[74:77], v[22:25], 0
	s_waitcnt lgkmcnt(4)
	v_mfma_f32_16x16x32_bf16 v[2:5], v[78:81], v[26:29], v[2:5]
	v_mfma_f32_16x16x32_bf16 v[6:9], v[78:81], v[30:33], v[6:9]
	s_waitcnt lgkmcnt(2)
	v_mfma_f32_16x16x32_bf16 v[2:5], v[70:73], v[34:37], v[2:5]
	v_mfma_f32_16x16x32_bf16 v[6:9], v[70:73], v[38:41], v[6:9]
	s_waitcnt lgkmcnt(0)
	v_mfma_f32_16x16x32_bf16 v[2:5], v[66:69], v[42:45], v[2:5]
	v_mfma_f32_16x16x32_bf16 v[6:9], v[66:69], v[46:49], v[6:9]
	s_waitcnt vmcnt(15)
	v_add_u32_e32 v208, s100, v206
	v_add_u32_e32 v209, s100, v207
	v_add_u32_e32 v214, s100, v210
	v_add_u32_e32 v215, s100, v211
	v_add_u32_e32 v216, s100, v212
	v_add_u32_e32 v217, s100, v213
	ds_read_b128 v[118:121], v208
	ds_read_b128 v[114:117], v208 offset:1024
	ds_read_b128 v[102:105], v214
	ds_read_b128 v[98:101], v215
	ds_read_b32 v178, v209 offset:4096
	ds_read_b32 v156, v216 offset:4096
	ds_read_b32 v150, v217 offset:4096
	v_mul_f32_e64 v10, v110, v182
	v_mul_f32_e64 v11, v111, v182
	v_pk_mul_f32 v[12:13], v[112:113], v[182:183] op_sel_hi:[1,0]
	v_pk_fma_f32 v[2:3], v[144:145], v[10:11], v[2:3]
	v_pk_fma_f32 v[4:5], v[140:141], v[12:13], v[4:5]
	v_pk_mul_f32 v[10:11], v[2:3], v[236:237] op_sel_hi:[1,0]
	v_pk_mul_f32 v[12:13], v[4:5], v[236:237] op_sel_hi:[1,0]
	v_pk_mul_f32 v[10:11], v[2:3], v[10:11]
	v_pk_mul_f32 v[12:13], v[4:5], v[12:13]
	v_pk_fma_f32 v[10:11], v[2:3], v[10:11], v[2:3]
	v_pk_fma_f32 v[12:13], v[4:5], v[12:13], v[4:5]
	v_pk_mul_f32 v[10:11], v[10:11], v[238:239] op_sel_hi:[1,0]
	v_pk_mul_f32 v[12:13], v[12:13], v[238:239] op_sel_hi:[1,0]
	v_pk_mul_f32 v[10:11], v[10:11], v[242:243] op_sel_hi:[1,0]
	v_pk_mul_f32 v[12:13], v[12:13], v[242:243] op_sel_hi:[1,0]
	v_pk_mul_f32 v[10:11], v[10:11], v[244:245] op_sel_hi:[1,0]
	v_pk_mul_f32 v[12:13], v[12:13], v[244:245] op_sel_hi:[1,0]
	v_exp_f32_e32 v10, v10
	v_exp_f32_e32 v11, v11
	v_exp_f32_e32 v12, v12
	v_exp_f32_e32 v13, v13
	v_pk_add_f32 v[10:11], v[10:11], v[246:247] op_sel_hi:[1,0]
	v_pk_add_f32 v[12:13], v[12:13], v[246:247] op_sel_hi:[1,0]
	v_rcp_f32_e32 v10, v10
	v_rcp_f32_e32 v11, v11
	v_rcp_f32_e32 v12, v12
	v_rcp_f32_e32 v13, v13
	v_ashrrev_i32_e32 v185, 31, v184
	v_pk_mul_f32 v[2:3], v[2:3], v[10:11]
	s_add_i32 s3, s3, 16
	v_pk_mul_f32 v[4:5], v[4:5], v[12:13]
	v_cvt_pk_bf16_f32 v2, v2, v3
	v_cvt_pk_bf16_f32 v3, v4, v5
	v_pk_mul_f32 v[4:5], v[106:107], v[180:181] op_sel_hi:[1,0]
	v_pk_mul_f32 v[12:13], v[108:109], v[180:181] op_sel_hi:[1,0]
	v_pk_fma_f32 v[4:5], v[144:145], v[4:5], v[6:7]
	v_pk_fma_f32 v[8:9], v[140:141], v[12:13], v[8:9]
	v_lshlrev_b64 v[6:7], 13, v[184:185]
	v_lshl_add_u64 v[6:7], v[138:139], 0, v[6:7]
	global_store_dwordx2 v[6:7], v[2:3], off
	v_pk_mul_f32 v[10:11], v[4:5], v[236:237] op_sel_hi:[1,0]
	v_pk_mul_f32 v[12:13], v[8:9], v[236:237] op_sel_hi:[1,0]
	v_pk_mul_f32 v[10:11], v[4:5], v[10:11]
	v_pk_mul_f32 v[12:13], v[8:9], v[12:13]
	v_pk_fma_f32 v[10:11], v[4:5], v[10:11], v[4:5]
	v_pk_fma_f32 v[12:13], v[8:9], v[12:13], v[8:9]
	v_pk_mul_f32 v[10:11], v[10:11], v[238:239] op_sel_hi:[1,0]
	v_pk_mul_f32 v[12:13], v[12:13], v[238:239] op_sel_hi:[1,0]
	v_pk_mul_f32 v[10:11], v[10:11], v[242:243] op_sel_hi:[1,0]
	v_pk_mul_f32 v[12:13], v[12:13], v[242:243] op_sel_hi:[1,0]
	v_pk_mul_f32 v[10:11], v[10:11], v[244:245] op_sel_hi:[1,0]
	v_pk_mul_f32 v[12:13], v[12:13], v[244:245] op_sel_hi:[1,0]
	v_exp_f32_e32 v10, v10
	v_exp_f32_e32 v11, v11
	v_exp_f32_e32 v12, v12
	v_exp_f32_e32 v13, v13
	v_pk_add_f32 v[10:11], v[10:11], v[246:247] op_sel_hi:[1,0]
	v_pk_add_f32 v[12:13], v[12:13], v[246:247] op_sel_hi:[1,0]
	v_rcp_f32_e32 v10, v10
	v_rcp_f32_e32 v11, v11
	v_rcp_f32_e32 v12, v12
	v_rcp_f32_e32 v13, v13
	v_add_u32_e32 v6, 8, v184
	v_pk_mul_f32 v[2:3], v[4:5], v[10:11]
	v_pk_mul_f32 v[4:5], v[8:9], v[12:13]
	v_ashrrev_i32_e32 v7, 31, v6
	v_cvt_pk_bf16_f32 v2, v2, v3
	v_cvt_pk_bf16_f32 v3, v4, v5
	v_lshlrev_b64 v[4:5], 13, v[6:7]
	v_lshl_add_u64 v[4:5], v[138:139], 0, v[4:5]
	global_store_dwordx2 v[4:5], v[2:3], off
	s_waitcnt lgkmcnt(0)
	v_mov_b64_e32 v[6:7], v[118:119]
	v_mov_b64_e32 v[2:3], v[114:115]
	v_lshl_add_u64 v[170:171], v[170:171], 0, 64
	v_lshl_add_u64 v[172:173], v[172:173], 0, 64
	v_lshl_add_u64 v[174:175], v[174:175], 0, 64
	s_cmpk_lg_i32 s3, 0x7f0
	v_mov_b64_e32 v[8:9], v[120:121]
	v_mov_b64_e32 v[4:5], v[116:117]
	s_cbranch_scc1 .LBB0_87
	s_branch .Lssm_after
.Lssm_warm:
	v_add_u32_e32 v234, s3, v162
	v_add_u32_e32 v226, 96, v234
	v_mov_b32_e32 v222, s10
	v_mov_b32_e32 v223, s8
	v_add_u32_e32 v227, 0xffffe060, v234
	v_cmp_gt_i32_e32 vcc, s26, v226
	v_ashrrev_i32_e32 v228, 31, v226
	v_mov_b32_e32 v224, s11
	v_mov_b32_e32 v225, s9
	v_cndmask_b32_e32 v230, v222, v223, vcc
	v_cndmask_b32_e32 v222, v227, v226, vcc
	v_cndmask_b32_e32 v223, 0, v228, vcc
	v_cndmask_b32_e32 v231, v224, v225, vcc
	v_lshlrev_b64 v[232:233], 14, v[222:223]
	v_lshl_add_u64 v[230:231], v[230:231], 0, v[232:233]
	v_lshl_add_u64 v[200:201], v[230:231], 0, s[36:37]
	v_lshl_add_u64 v[200:201], v[200:201], 0, v[124:125]
	s_add_i32 m0, s100, 0x1000
	s_nop 0
	global_load_lds_dword v[174:175], off
	s_add_i32 m0, s100, 0x3f0
	s_nop 0
	global_load_lds_dwordx4 v[200:201], off offset:16
	s_add_i32 m0, s100, 0x0
	s_nop 0
	global_load_lds_dwordx4 v[200:201], off
	s_nop 0
	s_add_i32 s98, s98, 0x1400
	s_cmp_eq_u32 s98, 0x7800
	s_cselect_b32 s98, 0, s98
	s_add_i32 s100, s99, s98
